# diff fast tile loop body aligned to a 64-byte boundary (padding in unreachable gaps, downstream code phase kept)
# speedup vs baseline: 1.0041x; 1.0041x over previous
.Lf_to463:
	ds_read_b64_tr_b16 v[180:181], v0 offset:16384
	ds_read_b64_tr_b16 v[182:183], v0 offset:16896
	ds_read_b64_tr_b16 v[230:231], v0 offset:17408
	ds_read_b64_tr_b16 v[232:233], v0 offset:17920
	s_mov_b32 s62, s60
	s_mov_b32 s63, s60
	s_waitcnt lgkmcnt(2)
	v_mfma_f32_32x32x16_bf16 v[64:79], v[180:183], v[140:143], v[64:79]
	s_mov_b32 s61, s60
	v_max_f32_e32 v15, v14, v14
	v_max_f32_e32 v218, v209, v209
	v_max_f32_e32 v15, v218, v15
	v_cndmask_b32_e64 v15, v14, v15, s[4:5]
	v_sub_f32_e32 v14, v209, v15
	v_exp_f32_e32 v14, v14
	s_waitcnt lgkmcnt(0)
	v_mfma_f32_32x32x16_bf16 v[64:79], v[230:233], v[136:139], v[64:79]
	ds_read_b64_tr_b16 v[180:181], v0 offset:18432
	ds_read_b64_tr_b16 v[182:183], v0 offset:18944
	ds_read_b64_tr_b16 v[230:231], v0 offset:19456
	ds_read_b64_tr_b16 v[232:233], v0 offset:19968
	v_mov_b32_e32 v209, v15
	v_cndmask_b32_e64 v14, 0, v14, s[4:5]
	s_mov_b64 s[4:5], -1
	s_waitcnt lgkmcnt(2)
	v_mfma_f32_32x32x16_bf16 v[64:79], v[180:183], v[132:135], v[64:79]
	s_waitcnt lgkmcnt(0)
	v_mfma_f32_32x32x16_bf16 v[64:79], v[230:233], v[128:131], v[64:79]
	ds_read_b64_tr_b16 v[180:181], v0 offset:20480
	ds_read_b64_tr_b16 v[182:183], v0 offset:20992
	ds_read_b64_tr_b16 v[230:231], v0 offset:21504
	ds_read_b64_tr_b16 v[232:233], v0 offset:22016
	s_waitcnt lgkmcnt(2)
	v_mfma_f32_32x32x16_bf16 v[48:63], v[180:183], v[140:143], v[48:63]
	s_nop 5
	v_mul_f32_e64 v78, v14, v78
	v_mul_f32_e64 v79, v14, v79
	v_mul_f32_e64 v76, v14, v76
	v_mul_f32_e64 v77, v14, v77
	v_mul_f32_e64 v74, v14, v74
	v_mul_f32_e64 v75, v14, v75
	v_pk_mul_f32 v[72:73], v[14:15], v[72:73] op_sel_hi:[0,1]
	v_pk_mul_f32 v[70:71], v[14:15], v[70:71] op_sel_hi:[0,1]
	v_pk_mul_f32 v[68:69], v[14:15], v[68:69] op_sel_hi:[0,1]
	v_pk_mul_f32 v[66:67], v[14:15], v[66:67] op_sel_hi:[0,1]
	s_waitcnt lgkmcnt(0)
	v_mfma_f32_32x32x16_bf16 v[48:63], v[230:233], v[136:139], v[48:63]
	ds_read_b64_tr_b16 v[180:181], v0 offset:22528
	ds_read_b64_tr_b16 v[182:183], v0 offset:23040
	ds_read_b64_tr_b16 v[230:231], v0 offset:23552
	ds_read_b64_tr_b16 v[232:233], v0 offset:24064
	v_mul_f32_e64 v64, v14, v64
	v_mul_f32_e64 v65, v14, v65
	s_waitcnt lgkmcnt(2)
	v_mfma_f32_32x32x16_bf16 v[48:63], v[180:183], v[132:135], v[48:63]
	s_waitcnt lgkmcnt(0)
	v_mfma_f32_32x32x16_bf16 v[48:63], v[230:233], v[128:131], v[48:63]
	ds_read_b64_tr_b16 v[180:181], v0 offset:24576
	ds_read_b64_tr_b16 v[182:183], v0 offset:25088
	ds_read_b64_tr_b16 v[230:231], v0 offset:25600
	ds_read_b64_tr_b16 v[232:233], v0 offset:26112
	s_waitcnt lgkmcnt(2)
	v_mfma_f32_32x32x16_bf16 v[32:47], v[180:183], v[140:143], v[32:47]
	s_nop 5
	v_mul_f32_e64 v62, v14, v62
	v_mul_f32_e64 v63, v14, v63
	v_mul_f32_e64 v60, v14, v60
	v_mul_f32_e64 v61, v14, v61
	v_mul_f32_e64 v58, v14, v58
	v_mul_f32_e64 v59, v14, v59
	v_pk_mul_f32 v[56:57], v[14:15], v[56:57] op_sel_hi:[0,1]
	v_pk_mul_f32 v[54:55], v[14:15], v[54:55] op_sel_hi:[0,1]
	v_pk_mul_f32 v[52:53], v[14:15], v[52:53] op_sel_hi:[0,1]
	v_pk_mul_f32 v[50:51], v[14:15], v[50:51] op_sel_hi:[0,1]
	s_waitcnt lgkmcnt(0)
	v_mfma_f32_32x32x16_bf16 v[32:47], v[230:233], v[136:139], v[32:47]
	ds_read_b64_tr_b16 v[180:181], v0 offset:26624
	ds_read_b64_tr_b16 v[182:183], v0 offset:27136
	ds_read_b64_tr_b16 v[230:231], v0 offset:27648
	ds_read_b64_tr_b16 v[232:233], v0 offset:28160
	v_mul_f32_e64 v48, v14, v48
	v_mul_f32_e64 v49, v14, v49
	s_waitcnt lgkmcnt(2)
	v_mfma_f32_32x32x16_bf16 v[32:47], v[180:183], v[132:135], v[32:47]
	s_waitcnt lgkmcnt(0)
	v_mfma_f32_32x32x16_bf16 v[32:47], v[230:233], v[128:131], v[32:47]
	ds_read_b64_tr_b16 v[180:181], v0 offset:28672
	ds_read_b64_tr_b16 v[182:183], v0 offset:29184
	ds_read_b64_tr_b16 v[230:231], v0 offset:29696
	ds_read_b64_tr_b16 v[232:233], v0 offset:30208
	s_waitcnt lgkmcnt(2)
	v_mfma_f32_32x32x16_bf16 v[16:31], v[180:183], v[140:143], v[16:31]
	ds_read_b64_tr_b16 v[180:181], v0 offset:30720
	ds_read_b64_tr_b16 v[182:183], v0 offset:31232
	ds_read_b64_tr_b16 v[234:235], v0 offset:31744
	ds_read_b64_tr_b16 v[236:237], v0 offset:32256
	s_nop 1
	v_mul_f32_e64 v46, v14, v46
	v_mul_f32_e64 v47, v14, v47
	v_pk_mul_f32 v[44:45], v[14:15], v[44:45] op_sel_hi:[0,1]
	v_pk_mul_f32 v[42:43], v[14:15], v[42:43] op_sel_hi:[0,1]
	v_pk_mul_f32 v[40:41], v[14:15], v[40:41] op_sel_hi:[0,1]
	v_pk_mul_f32 v[38:39], v[14:15], v[38:39] op_sel_hi:[0,1]
	v_pk_mul_f32 v[36:37], v[14:15], v[36:37] op_sel_hi:[0,1]
	s_waitcnt lgkmcnt(4)
	v_mfma_f32_32x32x16_bf16 v[16:31], v[230:233], v[136:139], v[16:31]
	v_mul_f32_e64 v34, v14, v34
	v_mul_f32_e64 v35, v14, v35
	v_mul_f32_e64 v32, v14, v32
	v_mul_f32_e64 v33, v14, v33
	s_waitcnt lgkmcnt(2)
	v_mfma_f32_32x32x16_bf16 v[16:31], v[180:183], v[132:135], v[16:31]
	v_mov_b64_e32 v[182:183], s[62:63]
	v_mov_b64_e32 v[180:181], s[60:61]
	s_nop 1
	v_mfma_f32_32x32x16_bf16 v[80:95], v[180:183], v[140:143], v[80:95]
	v_mov_b32_e32 v140, 0
	v_mov_b32_e32 v141, v140
	v_mov_b32_e32 v142, v140
	v_mov_b32_e32 v143, v140
	v_mfma_f32_32x32x16_bf16 v[80:95], v[180:183], v[136:139], v[80:95]
	v_mov_b32_e32 v136, v140
	v_mov_b32_e32 v137, v140
	v_mov_b32_e32 v138, v140
	v_mov_b32_e32 v139, v140
	v_mfma_f32_32x32x16_bf16 v[80:95], v[180:183], v[132:135], v[80:95]
	v_mov_b32_e32 v132, v140
	v_mov_b32_e32 v133, v140
	v_mov_b32_e32 v134, v140
	v_mov_b32_e32 v135, v140
	s_waitcnt lgkmcnt(0)
	v_mfma_f32_32x32x16_bf16 v[16:31], v[234:237], v[128:131], v[16:31]
	v_mfma_f32_32x32x16_bf16 v[80:95], v[180:183], v[128:131], v[80:95]
	s_nop 10
	v_mul_f32_e64 v30, v14, v30
	v_mul_f32_e64 v31, v14, v31
	v_mul_f32_e64 v28, v14, v28
	v_mul_f32_e64 v29, v14, v29
	v_mul_f32_e64 v26, v14, v26
	v_mul_f32_e64 v27, v14, v27
	v_pk_mul_f32 v[24:25], v[14:15], v[24:25] op_sel_hi:[0,1]
	v_pk_mul_f32 v[22:23], v[14:15], v[22:23] op_sel_hi:[0,1]
	v_pk_mul_f32 v[20:21], v[14:15], v[20:21] op_sel_hi:[0,1]
	v_pk_mul_f32 v[18:19], v[14:15], v[18:19] op_sel_hi:[0,1]
	v_pk_mul_f32 v[16:17], v[14:15], v[16:17] op_sel_hi:[0,1]
	v_pk_mul_f32 v[94:95], v[14:15], v[94:95] op_sel_hi:[0,1]
	v_pk_mul_f32 v[92:93], v[14:15], v[92:93] op_sel_hi:[0,1]
	v_pk_mul_f32 v[90:91], v[14:15], v[90:91] op_sel_hi:[0,1]
	v_pk_mul_f32 v[88:89], v[14:15], v[88:89] op_sel_hi:[0,1]
	v_pk_mul_f32 v[86:87], v[14:15], v[86:87] op_sel_hi:[0,1]
	v_pk_mul_f32 v[84:85], v[14:15], v[84:85] op_sel_hi:[0,1]
	v_pk_mul_f32 v[82:83], v[14:15], v[82:83] op_sel_hi:[0,1]
	v_pk_mul_f32 v[80:81], v[14:15], v[80:81] op_sel_hi:[0,1]
	v_mov_b32_e32 v128, v140
	v_mov_b32_e32 v129, v140
	v_mov_b32_e32 v130, v140
	v_mov_b32_e32 v131, v140
	s_branch .LBB0_459
	.p2align 6

.Lf_462:
	s_and_b32 s17, s19, 0x18000
	v_add_u32_e32 v0, s17, v227
	v_add_u32_e32 v2, v0, v228
	ds_read_b128 v[96:99], v2
	ds_read_b128 v[100:103], v2 offset:4096
	v_add_u32_e32 v2, v0, v226
	ds_read_b128 v[180:183], v2
	ds_read_b128 v[230:233], v2 offset:4096
	v_add_u32_e32 v2, v0, v225
	v_add_u32_e32 v0, v0, v224
	s_min_u32 s16, s28, 1
	ds_read_b128 v[234:237], v2
	ds_read_b128 v[238:241], v2 offset:4096
	ds_read_b128 v[242:245], v0
	ds_read_b128 v[246:249], v0 offset:4096
	s_lshl_b32 s16, s16, 15
	s_sub_i32 s16, s19, s16
	s_and_b32 s16, s16, 0x18000
	v_add_u32_e32 v0, s16, v195
	s_setprio 1
	s_waitcnt lgkmcnt(6)
	v_mfma_f32_32x32x16_bf16 v[112:127], v[96:99], v[156:159], 0
	s_add_i32 s22, s13, 1
	s_add_i32 s61, s19, 0x8000
	s_add_i32 s20, s61, 0x10000
	s_and_b32 s20, s20, 0x18000
	v_mfma_f32_32x32x16_bf16 v[96:111], v[100:103], v[156:159], 0
	s_add_i32 s20, s20, s23
	s_add_i32 s62, s22, -2
	s_cmpk_gt_u32 s62, 0x41
	s_cselect_b32 s61, 1, 0
	s_waitcnt lgkmcnt(4)
	v_mfma_f32_32x32x16_bf16 v[112:127], v[180:183], v[152:155], v[112:127]
	s_cmp_lt_u32 s62, 62
	s_cselect_b32 s16, 0, 0xffffffc0
	s_cselect_b32 s17, s9, s10
	s_add_i32 s16, s16, s22
	v_mfma_f32_32x32x16_bf16 v[96:111], v[230:233], v[152:155], v[96:111]
	s_lshl_b32 s16, s16, 6
	s_add_i32 s62, s16, s17
	s_ashr_i32 s63, s62, 31
	s_add_u32 s30, s62, s11
	s_waitcnt lgkmcnt(2)
	v_mfma_f32_32x32x16_bf16 v[112:127], v[234:237], v[148:151], v[112:127]
	s_addc_u32 s31, s63, 0
	s_lshl_b64 s[30:31], s[30:31], 7
	s_add_u32 s34, s95, s30
	s_addc_u32 s35, s3, s31
	v_mfma_f32_32x32x16_bf16 v[96:111], v[238:241], v[148:151], v[96:111]
	s_add_u32 s16, s62, s12
	s_addc_u32 s17, s63, 0
	s_lshl_b64 s[16:17], s[16:17], 7
	s_add_u32 s16, s95, s16
	s_waitcnt lgkmcnt(0)
	v_mfma_f32_32x32x16_bf16 v[112:127], v[242:245], v[144:147], v[112:127]
	s_addc_u32 s17, s3, s17
	s_add_u32 s30, s14, s30
	s_addc_u32 s31, s15, s31
	v_mfma_f32_32x32x16_bf16 v[96:111], v[246:249], v[144:147], v[96:111]
	ds_read_b64_tr_b16 v[176:177], v0 offset:16384
	ds_read_b64_tr_b16 v[178:179], v0 offset:16896
	ds_read_b64_tr_b16 v[172:173], v0 offset:17408
	ds_read_b64_tr_b16 v[174:175], v0 offset:17920
	ds_read_b64_tr_b16 v[168:169], v0 offset:18432
	ds_read_b64_tr_b16 v[170:171], v0 offset:18944
	ds_read_b64_tr_b16 v[164:165], v0 offset:19456
	ds_read_b64_tr_b16 v[166:167], v0 offset:19968
	ds_read_b64_tr_b16 v[160:161], v0 offset:20480
	ds_read_b64_tr_b16 v[162:163], v0 offset:20992
	ds_read_b64_tr_b16 v[10:11], v0 offset:21504
	ds_read_b64_tr_b16 v[12:13], v0 offset:22016
	ds_read_b64_tr_b16 v[6:7], v0 offset:22528
	ds_read_b64_tr_b16 v[8:9], v0 offset:23040
	ds_read_b64_tr_b16 v[2:3], v0 offset:23552
	ds_read_b64_tr_b16 v[4:5], v0 offset:24064
	s_setprio 0
	v_max3_f32 v14, v112, v113, v114
	v_max3_f32 v15, v115, v116, v117
	v_max3_f32 v180, v118, v119, v120
	v_max3_f32 v181, v121, v122, v123
	v_max3_f32 v182, v124, v125, v126
	v_max3_f32 v183, v96, v97, v98
	v_max3_f32 v230, v99, v100, v101
	v_max3_f32 v231, v102, v103, v104
	s_nop 0
	v_max3_f32 v14, v14, v15, v180
	v_max3_f32 v232, v105, v106, v107
	v_max3_f32 v15, v181, v182, v127
	v_max3_f32 v233, v108, v109, v110
	v_max3_f32 v180, v183, v230, v231
	v_max3_f32 v181, v232, v233, v111
	s_nop 0
	v_max3_f32 v14, v14, v15, v180
	v_max_f32_e32 v14, v14, v181
	v_mov_b32_e32 v15, v14
	s_nop 1
	v_permlane32_swap_b32_e32 v15, v14
	v_max_f32_e32 v14, v14, v15
	v_cmp_lt_f32_e32 vcc, 0x42800000, v14
	s_waitcnt lgkmcnt(0)
	s_cbranch_vccz .Lf_459
	s_branch .Lf_to463
	.p2align 6
